# GU loop DMA 4/4 split, mid-block setprio removed, Down epilogue: removed conservative vmcnt waits before residual loads
# speedup vs baseline: 1.0015x; 1.0015x over previous
; #define PG8_STAGE(bufoff, gbase, voff) do { _Pragma("unroll") for (int _i = 0; _i < 2; ++_i) \
;         __builtin_amdgcn_global_load_lds((const unsigned*)((const char*)(gbase) + (voff)[_i]), (PG8_LAS unsigned*)(lds + (bufoff) + ldsw + _i * 8192), 16, 0, 0); } while (0)
; #define PG8_LDA(dst, b, h) do { _Pragma("unroll") for (int m = 0; m < 4; ++m) _Pragma("unroll") for (int k = 0; k < 2; ++k) dst[m][k] = *(const PG8_LAS bf16x8*)(lds + PG8_SA(b, h) + aoff + m * 2048 + k * 1024); } while (0)
; #define PG8_LDB(dst, b, h) do { _Pragma("unroll") for (int n = 0; n < 2; ++n) _Pragma("unroll") for (int k = 0; k < 2; ++k) dst[n][k] = *(const PG8_LAS bf16x8*)(lds + PG8_SB(b, h) + boff + n * 2048 + k * 1024); } while (0)
; #define PG8_MMA(ai, bj, At, Bt) do { __builtin_amdgcn_s_setprio(1); _Pragma("unroll") for (int m = 0; m < 4; ++m) _Pragma("unroll") for (int n = 0; n < 2; ++n) _Pragma("unroll") for (int k = 0; k < 2; ++k) \
;         acc[ai][bj][m][n] = __builtin_amdgcn_mfma_f32_16x16x32_bf16(Bt[n][k], At[m][k], acc[ai][bj][m][n], 0, 0, 0); __builtin_amdgcn_s_setprio(0); } while (0)
; #define PG8_WAIT_V(n) asm volatile("s_waitcnt vmcnt(" #n ")" ::: "memory")
; #define PG8_WAIT_L(n) asm volatile("s_waitcnt lgkmcnt(" #n ")" ::: "memory")
; template <class Epi, class Sched, bool ALIGN_EPI = false, bool SP2 = true>
; __device__ __forceinline__ void gemm_phase(PG8_LAS unsigned char* lds, const Gemm g, const Sched& S, const Epi& E) {
;     ...
;             const bool last = (t == nt - 2);
;             const char* a1 = cA + (size_t)(t + 1) * kstepA;
;             const char* a2 = last ? nA : cA + (size_t)(t + 2) * kstepA; const char* b2 = last ? nB : cB + (size_t)(t + 2) * kstep;
;             const char* a3 = a2 + kstepA; const char* b3 = b2 + kstep;
;             if (last && has_next) S.a_ready(nxt);
;             if constexpr (SP2) {
;             PG8_LDB(B0, 0, 0); PG8_LDB(B1, 0, 1); PG8_SCHED; PG8_LDA(At, 0, 0); PG8_STAGE(PG8_SA(1, 1), a1 + hstepA, voffA);
;             PG8_WAIT_V(8); PG8_WAIT_L(0); PG8_BAR; PG8_MMA(0, 0, At, B0); PG8_MMA(0, 1, At, B1); PG8_BAR; PG8_SCHED;
;             PG8_LDA(At, 0, 1); PG8_STAGE(PG8_SB(0, 0), b2, voffB); PG8_STAGE(PG8_SB(0, 1), b2 + hstep, voffB); PG8_STAGE(PG8_SA(0, 0), a2, voffA);
;             PG8_WAIT_V(8); PG8_WAIT_L(0); PG8_BAR; PG8_MMA(1, 0, At, B0); PG8_MMA(1, 1, At, B1); PG8_BAR; PG8_SCHED;
.LBB0_128:
	s_add_u32 s14, s46, 0xfffc0080
	s_addc_u32 s15, s47, -1
	s_add_i32 s70, 0, 0x10000
	s_cmp_eq_u32 s60, 12
	s_cselect_b32 s51, s17, s15
	s_cselect_b32 s50, s39, s14
	v_add_u32_e32 v141, s70, v147
	s_cselect_b32 s49, s25, s7
	s_cselect_b32 s48, s59, s6
	s_add_i32 s71, 0, 0x14000
	ds_read_b128 v[152:155], v141
	ds_read_b128 v[156:159], v141 offset:1024
	ds_read_b128 v[160:163], v141 offset:2048
	ds_read_b128 v[164:167], v141 offset:3072
	v_add_u32_e32 v141, s71, v147
	ds_read_b128 v[168:171], v141
	ds_read_b128 v[172:175], v141 offset:1024
	ds_read_b128 v[176:179], v141 offset:2048
	ds_read_b128 v[180:183], v141 offset:3072
	s_add_u32 s14, s6, 0x3ff80
	s_addc_u32 s15, s7, 0
	v_lshl_add_u64 v[148:149], s[14:15], 0, v[132:133]
	s_add_i32 m0, s28, 0x1c000
	ds_read_b128 v[184:187], v150
	ds_read_b128 v[188:191], v150 offset:1024
	ds_read_b128 v[200:203], v150 offset:2048
	ds_read_b128 v[204:207], v150 offset:3072
	ds_read_b128 v[208:211], v150 offset:4096
	ds_read_b128 v[212:215], v150 offset:5120
	ds_read_b128 v[216:219], v150 offset:6144
	ds_read_b128 v[220:223], v150 offset:7168
	global_load_lds_dwordx4 v[148:149], off
	v_lshl_add_u64 v[148:149], s[14:15], 0, v[128:129]
	s_add_i32 m0, s28, 0x1e000
	s_nop 0
	global_load_lds_dwordx4 v[148:149], off
	v_lshl_add_u64 v[148:149], s[46:47], 0, v[136:137]
	s_add_i32 m0, s29, 0xc000
	s_nop 0
	global_load_lds_dwordx4 v[148:149], off
	v_lshl_add_u64 v[148:149], s[46:47], 0, v[138:139]
	s_add_i32 m0, s29, 0xe000
	s_nop 0
	global_load_lds_dwordx4 v[148:149], off
	s_waitcnt vmcnt(8)
	s_waitcnt lgkmcnt(0)
	s_barrier
	s_setprio 1
	s_waitcnt lgkmcnt(0)
	v_mfma_f32_16x16x32_bf16 v[120:123], v[152:155], v[184:187], v[120:123]
	v_mfma_f32_16x16x32_bf16 v[112:115], v[160:163], v[184:187], v[112:115]
	v_mfma_f32_16x16x32_bf16 v[108:111], v[152:155], v[200:203], v[108:111]
	v_mfma_f32_16x16x32_bf16 v[96:99], v[160:163], v[200:203], v[96:99]
	v_mfma_f32_16x16x32_bf16 v[92:95], v[152:155], v[208:211], v[92:95]
	v_mfma_f32_16x16x32_bf16 v[80:83], v[160:163], v[208:211], v[80:83]
	v_mfma_f32_16x16x32_bf16 v[76:79], v[152:155], v[216:219], v[76:79]
	v_mfma_f32_16x16x32_bf16 v[64:67], v[160:163], v[216:219], v[64:67]
	v_mfma_f32_16x16x32_bf16 v[120:123], v[156:159], v[188:191], v[120:123]
	v_mfma_f32_16x16x32_bf16 v[112:115], v[164:167], v[188:191], v[112:115]
	v_mfma_f32_16x16x32_bf16 v[108:111], v[156:159], v[204:207], v[108:111]
	v_mfma_f32_16x16x32_bf16 v[96:99], v[164:167], v[204:207], v[96:99]
	v_mfma_f32_16x16x32_bf16 v[92:95], v[156:159], v[212:215], v[92:95]
	v_mfma_f32_16x16x32_bf16 v[80:83], v[164:167], v[212:215], v[80:83]
	v_mfma_f32_16x16x32_bf16 v[76:79], v[156:159], v[220:223], v[76:79]
	v_mfma_f32_16x16x32_bf16 v[64:67], v[164:167], v[220:223], v[64:67]
	v_mfma_f32_16x16x32_bf16 v[124:127], v[168:171], v[184:187], v[124:127]
	v_mfma_f32_16x16x32_bf16 v[116:119], v[176:179], v[184:187], v[116:119]
	v_mfma_f32_16x16x32_bf16 v[104:107], v[168:171], v[200:203], v[104:107]
	v_mfma_f32_16x16x32_bf16 v[100:103], v[176:179], v[200:203], v[100:103]
	v_mfma_f32_16x16x32_bf16 v[88:91], v[168:171], v[208:211], v[88:91]
	v_mfma_f32_16x16x32_bf16 v[84:87], v[176:179], v[208:211], v[84:87]
	v_mfma_f32_16x16x32_bf16 v[72:75], v[168:171], v[216:219], v[72:75]
	v_mfma_f32_16x16x32_bf16 v[68:71], v[176:179], v[216:219], v[68:71]
	v_mfma_f32_16x16x32_bf16 v[124:127], v[172:175], v[188:191], v[124:127]
	v_mfma_f32_16x16x32_bf16 v[116:119], v[180:183], v[188:191], v[116:119]
	v_mfma_f32_16x16x32_bf16 v[104:107], v[172:175], v[204:207], v[104:107]
	v_mfma_f32_16x16x32_bf16 v[100:103], v[180:183], v[204:207], v[100:103]
	v_mfma_f32_16x16x32_bf16 v[88:91], v[172:175], v[212:215], v[88:91]
	v_mfma_f32_16x16x32_bf16 v[84:87], v[180:183], v[212:215], v[84:87]
	v_mfma_f32_16x16x32_bf16 v[72:75], v[172:175], v[220:223], v[72:75]
	v_mfma_f32_16x16x32_bf16 v[68:71], v[180:183], v[220:223], v[68:71]
	s_setprio 0
	s_barrier
	s_add_i32 s14, s70, s28
	v_lshl_add_u64 v[148:149], s[48:49], 0, v[132:133]
	s_mov_b32 m0, s14
	ds_read_b128 v[184:187], v150 offset:16384
	ds_read_b128 v[188:191], v150 offset:17408
	ds_read_b128 v[200:203], v150 offset:18432
	ds_read_b128 v[204:207], v150 offset:19456
	ds_read_b128 v[208:211], v150 offset:20480
	ds_read_b128 v[212:215], v150 offset:21504
	ds_read_b128 v[216:219], v150 offset:22528
	ds_read_b128 v[220:223], v150 offset:23552
	global_load_lds_dwordx4 v[148:149], off
	s_add_i32 m0, s14, 0x2000
	v_lshl_add_u64 v[224:225], s[48:49], 0, v[128:129]
	global_load_lds_dwordx4 v[224:225], off
	v_lshl_add_u64 v[234:235], s[50:51], 0, v[130:131]
	v_lshl_add_u64 v[226:227], s[50:51], 0, v[134:135]
	s_mov_b32 m0, s29
	s_nop 0
	global_load_lds_dwordx4 v[226:227], off
	s_mov_b32 m0, s30
	s_nop 0
	global_load_lds_dwordx4 v[234:235], off
	s_waitcnt vmcnt(6)
	s_waitcnt lgkmcnt(0)
	s_barrier
; #define PG8_STAGE(bufoff, gbase, voff) do { _Pragma("unroll") for (int _i = 0; _i < 2; ++_i) \
;         __builtin_amdgcn_global_load_lds((const unsigned*)((const char*)(gbase) + (voff)[_i]), (PG8_LAS unsigned*)(lds + (bufoff) + ldsw + _i * 8192), 16, 0, 0); } while (0)
; #define PG8_LDA(dst, b, h) do { _Pragma("unroll") for (int m = 0; m < 4; ++m) _Pragma("unroll") for (int k = 0; k < 2; ++k) dst[m][k] = *(const PG8_LAS bf16x8*)(lds + PG8_SA(b, h) + aoff + m * 2048 + k * 1024); } while (0)
; #define PG8_LDB(dst, b, h) do { _Pragma("unroll") for (int n = 0; n < 2; ++n) _Pragma("unroll") for (int k = 0; k < 2; ++k) dst[n][k] = *(const PG8_LAS bf16x8*)(lds + PG8_SB(b, h) + boff + n * 2048 + k * 1024); } while (0)
; #define PG8_MMA(ai, bj, At, Bt) do { __builtin_amdgcn_s_setprio(1); _Pragma("unroll") for (int m = 0; m < 4; ++m) _Pragma("unroll") for (int n = 0; n < 2; ++n) _Pragma("unroll") for (int k = 0; k < 2; ++k) \
;         acc[ai][bj][m][n] = __builtin_amdgcn_mfma_f32_16x16x32_bf16(Bt[n][k], At[m][k], acc[ai][bj][m][n], 0, 0, 0); __builtin_amdgcn_s_setprio(0); } while (0)
; #define PG8_WAIT_V(n) asm volatile("s_waitcnt vmcnt(" #n ")" ::: "memory")
; #define PG8_WAIT_L(n) asm volatile("s_waitcnt lgkmcnt(" #n ")" ::: "memory")
; #define PG8_BAR __builtin_amdgcn_s_barrier()
; #define PG8_SCHED __builtin_amdgcn_sched_barrier(0)
; template <class Epi, class Sched, bool ALIGN_EPI = false, bool SP2 = true>
; __device__ __forceinline__ void gemm_phase(PG8_LAS unsigned char* lds, const Gemm g, const Sched& S, const Epi& E) {
;     ...
;             PG8_WAIT_V(8); PG8_WAIT_L(0); PG8_BAR; PG8_MMA(1, 0, At, B0); PG8_MMA(1, 1, At, B1); PG8_BAR; PG8_SCHED;
;             PG8_LDB(B0, 1, 0); PG8_LDB(B1, 1, 1); PG8_SCHED; PG8_LDA(At, 1, 0); PG8_STAGE(PG8_SA(0, 1), a2 + hstepA, voffA);
;             PG8_WAIT_V(8); PG8_WAIT_L(0); PG8_BAR; PG8_MMA(0, 0, At, B0); PG8_MMA(0, 1, At, B1); PG8_BAR; PG8_SCHED;
	s_setprio 1
	s_waitcnt lgkmcnt(0)
	v_mfma_f32_16x16x32_bf16 v[60:63], v[152:155], v[184:187], v[60:63]
	v_mfma_f32_16x16x32_bf16 v[48:51], v[160:163], v[184:187], v[48:51]
	v_mfma_f32_16x16x32_bf16 v[44:47], v[152:155], v[200:203], v[44:47]
	v_mfma_f32_16x16x32_bf16 v[32:35], v[160:163], v[200:203], v[32:35]
	v_mfma_f32_16x16x32_bf16 v[28:31], v[152:155], v[208:211], v[28:31]
	v_mfma_f32_16x16x32_bf16 v[16:19], v[160:163], v[208:211], v[16:19]
	v_mfma_f32_16x16x32_bf16 v[12:15], v[152:155], v[216:219], v[12:15]
	v_mfma_f32_16x16x32_bf16 v[4:7], v[160:163], v[216:219], v[4:7]
	v_mfma_f32_16x16x32_bf16 v[60:63], v[156:159], v[188:191], v[60:63]
	v_mfma_f32_16x16x32_bf16 v[48:51], v[164:167], v[188:191], v[48:51]
	v_mfma_f32_16x16x32_bf16 v[44:47], v[156:159], v[204:207], v[44:47]
	v_mfma_f32_16x16x32_bf16 v[32:35], v[164:167], v[204:207], v[32:35]
	v_mfma_f32_16x16x32_bf16 v[28:31], v[156:159], v[212:215], v[28:31]
	v_mfma_f32_16x16x32_bf16 v[16:19], v[164:167], v[212:215], v[16:19]
	v_mfma_f32_16x16x32_bf16 v[12:15], v[156:159], v[220:223], v[12:15]
	v_mfma_f32_16x16x32_bf16 v[4:7], v[164:167], v[220:223], v[4:7]
	v_mfma_f32_16x16x32_bf16 v[56:59], v[168:171], v[184:187], v[56:59]
	v_mfma_f32_16x16x32_bf16 v[52:55], v[176:179], v[184:187], v[52:55]
	v_mfma_f32_16x16x32_bf16 v[40:43], v[168:171], v[200:203], v[40:43]
	v_mfma_f32_16x16x32_bf16 v[36:39], v[176:179], v[200:203], v[36:39]
	v_mfma_f32_16x16x32_bf16 v[24:27], v[168:171], v[208:211], v[24:27]
	v_mfma_f32_16x16x32_bf16 v[20:23], v[176:179], v[208:211], v[20:23]
	v_mfma_f32_16x16x32_bf16 v[8:11], v[168:171], v[216:219], v[8:11]
	v_mfma_f32_16x16x32_bf16 v[0:3], v[176:179], v[216:219], v[0:3]
	v_mfma_f32_16x16x32_bf16 v[56:59], v[172:175], v[188:191], v[56:59]
	v_mfma_f32_16x16x32_bf16 v[52:55], v[180:183], v[188:191], v[52:55]
	v_mfma_f32_16x16x32_bf16 v[40:43], v[172:175], v[204:207], v[40:43]
	v_mfma_f32_16x16x32_bf16 v[36:39], v[180:183], v[204:207], v[36:39]
	v_mfma_f32_16x16x32_bf16 v[24:27], v[172:175], v[212:215], v[24:27]
	v_mfma_f32_16x16x32_bf16 v[20:23], v[180:183], v[212:215], v[20:23]
	v_mfma_f32_16x16x32_bf16 v[8:11], v[172:175], v[220:223], v[8:11]
	v_mfma_f32_16x16x32_bf16 v[0:3], v[180:183], v[220:223], v[0:3]
	s_setprio 0
	s_barrier
	s_add_i32 s70, 0, 0x18000
	v_add_u32_e32 v141, s70, v147
	s_add_i32 s71, 0, 0x1c000
	ds_read_b128 v[152:155], v141
	ds_read_b128 v[156:159], v141 offset:1024
	ds_read_b128 v[160:163], v141 offset:2048
	ds_read_b128 v[164:167], v141 offset:3072
	v_add_u32_e32 v141, s71, v147
	ds_read_b128 v[168:171], v141
	ds_read_b128 v[172:175], v141 offset:1024
	ds_read_b128 v[176:179], v141 offset:2048
	ds_read_b128 v[180:183], v141 offset:3072
	s_add_u32 s14, s48, 0x40000
	s_addc_u32 s15, s49, 0
	s_add_i32 m0, s28, 0x14000
	v_lshl_add_u64 v[236:237], s[14:15], 0, v[132:133]
	ds_read_b128 v[184:187], v150 offset:32768
	ds_read_b128 v[188:191], v150 offset:33792
	ds_read_b128 v[200:203], v150 offset:34816
	ds_read_b128 v[204:207], v150 offset:35840
	ds_read_b128 v[208:211], v150 offset:36864
	ds_read_b128 v[212:215], v150 offset:37888
	ds_read_b128 v[216:219], v150 offset:38912
	ds_read_b128 v[220:223], v150 offset:39936
	global_load_lds_dwordx4 v[236:237], off
	v_lshl_add_u64 v[236:237], s[14:15], 0, v[128:129]
	s_add_i32 m0, s28, 0x16000
	s_add_u32 s14, s50, 0x40000
	s_addc_u32 s15, s51, 0
	global_load_lds_dwordx4 v[236:237], off
	v_lshl_add_u64 v[236:237], s[14:15], 0, v[134:135]
	s_mov_b32 m0, s31
	s_nop 0
	global_load_lds_dwordx4 v[236:237], off
	v_lshl_add_u64 v[236:237], s[14:15], 0, v[130:131]
	s_mov_b32 m0, s34
	s_nop 0
	global_load_lds_dwordx4 v[236:237], off
	s_waitcnt vmcnt(8)
	s_waitcnt lgkmcnt(0)
	s_barrier
; #define PG8_STAGE(bufoff, gbase, voff) do { _Pragma("unroll") for (int _i = 0; _i < 2; ++_i) \
;         __builtin_amdgcn_global_load_lds((const unsigned*)((const char*)(gbase) + (voff)[_i]), (PG8_LAS unsigned*)(lds + (bufoff) + ldsw + _i * 8192), 16, 0, 0); } while (0)
; #define PG8_LDA(dst, b, h) do { _Pragma("unroll") for (int m = 0; m < 4; ++m) _Pragma("unroll") for (int k = 0; k < 2; ++k) dst[m][k] = *(const PG8_LAS bf16x8*)(lds + PG8_SA(b, h) + aoff + m * 2048 + k * 1024); } while (0)
; #define PG8_MMA(ai, bj, At, Bt) do { __builtin_amdgcn_s_setprio(1); _Pragma("unroll") for (int m = 0; m < 4; ++m) _Pragma("unroll") for (int n = 0; n < 2; ++n) _Pragma("unroll") for (int k = 0; k < 2; ++k) \
;         acc[ai][bj][m][n] = __builtin_amdgcn_mfma_f32_16x16x32_bf16(Bt[n][k], At[m][k], acc[ai][bj][m][n], 0, 0, 0); __builtin_amdgcn_s_setprio(0); } while (0)
; #define PG8_WAIT_V(n) asm volatile("s_waitcnt vmcnt(" #n ")" ::: "memory")
; #define PG8_WAIT_L(n) asm volatile("s_waitcnt lgkmcnt(" #n ")" ::: "memory")
; #define PG8_BAR __builtin_amdgcn_s_barrier()
; #define PG8_SCHED __builtin_amdgcn_sched_barrier(0)
; template <class Epi, class Sched, bool ALIGN_EPI = false, bool SP2 = true>
; __device__ __forceinline__ void gemm_phase(PG8_LAS unsigned char* lds, const Gemm g, const Sched& S, const Epi& E) {
;     ...
;         for (int t = 0; t < nt; t += 2) {
;     ...
;             PG8_WAIT_V(8); PG8_WAIT_L(0); PG8_BAR; PG8_MMA(0, 0, At, B0); PG8_MMA(0, 1, At, B1); PG8_BAR; PG8_SCHED;
;             PG8_LDA(At, 1, 1); PG8_STAGE(PG8_SB(1, 0), b3, voffB); PG8_STAGE(PG8_SB(1, 1), b3 + hstep, voffB); PG8_STAGE(PG8_SA(1, 0), a3, voffA);
;             PG8_WAIT_V(8); PG8_WAIT_L(0); PG8_BAR; PG8_MMA(1, 0, At, B0); PG8_MMA(1, 1, At, B1); PG8_BAR; PG8_SCHED;
	s_setprio 1
	s_waitcnt lgkmcnt(0)
	v_mfma_f32_16x16x32_bf16 v[120:123], v[152:155], v[184:187], v[120:123]
	v_mfma_f32_16x16x32_bf16 v[112:115], v[160:163], v[184:187], v[112:115]
	v_mfma_f32_16x16x32_bf16 v[108:111], v[152:155], v[200:203], v[108:111]
	v_mfma_f32_16x16x32_bf16 v[96:99], v[160:163], v[200:203], v[96:99]
	v_mfma_f32_16x16x32_bf16 v[92:95], v[152:155], v[208:211], v[92:95]
	v_mfma_f32_16x16x32_bf16 v[80:83], v[160:163], v[208:211], v[80:83]
	v_mfma_f32_16x16x32_bf16 v[76:79], v[152:155], v[216:219], v[76:79]
	v_mfma_f32_16x16x32_bf16 v[64:67], v[160:163], v[216:219], v[64:67]
	v_mfma_f32_16x16x32_bf16 v[120:123], v[156:159], v[188:191], v[120:123]
	v_mfma_f32_16x16x32_bf16 v[112:115], v[164:167], v[188:191], v[112:115]
	v_mfma_f32_16x16x32_bf16 v[108:111], v[156:159], v[204:207], v[108:111]
	v_mfma_f32_16x16x32_bf16 v[96:99], v[164:167], v[204:207], v[96:99]
	v_mfma_f32_16x16x32_bf16 v[92:95], v[156:159], v[212:215], v[92:95]
	v_mfma_f32_16x16x32_bf16 v[80:83], v[164:167], v[212:215], v[80:83]
	v_mfma_f32_16x16x32_bf16 v[76:79], v[156:159], v[220:223], v[76:79]
	v_mfma_f32_16x16x32_bf16 v[64:67], v[164:167], v[220:223], v[64:67]
	v_mfma_f32_16x16x32_bf16 v[124:127], v[168:171], v[184:187], v[124:127]
	v_mfma_f32_16x16x32_bf16 v[116:119], v[176:179], v[184:187], v[116:119]
	v_mfma_f32_16x16x32_bf16 v[104:107], v[168:171], v[200:203], v[104:107]
	v_mfma_f32_16x16x32_bf16 v[100:103], v[176:179], v[200:203], v[100:103]
	v_mfma_f32_16x16x32_bf16 v[88:91], v[168:171], v[208:211], v[88:91]
	v_mfma_f32_16x16x32_bf16 v[84:87], v[176:179], v[208:211], v[84:87]
	v_mfma_f32_16x16x32_bf16 v[72:75], v[168:171], v[216:219], v[72:75]
	v_mfma_f32_16x16x32_bf16 v[68:71], v[176:179], v[216:219], v[68:71]
	v_mfma_f32_16x16x32_bf16 v[124:127], v[172:175], v[188:191], v[124:127]
	v_mfma_f32_16x16x32_bf16 v[116:119], v[180:183], v[188:191], v[116:119]
	v_mfma_f32_16x16x32_bf16 v[104:107], v[172:175], v[204:207], v[104:107]
	v_mfma_f32_16x16x32_bf16 v[100:103], v[180:183], v[204:207], v[100:103]
	v_mfma_f32_16x16x32_bf16 v[88:91], v[172:175], v[212:215], v[88:91]
	v_mfma_f32_16x16x32_bf16 v[84:87], v[180:183], v[212:215], v[84:87]
	v_mfma_f32_16x16x32_bf16 v[72:75], v[172:175], v[220:223], v[72:75]
	v_mfma_f32_16x16x32_bf16 v[68:71], v[180:183], v[220:223], v[68:71]
	s_setprio 0
	s_barrier
	s_add_i32 s14, s70, s28
	v_lshl_add_u64 v[148:149], v[148:149], 0, s[18:19]
	s_mov_b32 m0, s14
	ds_read_b128 v[184:187], v150 offset:49152
	ds_read_b128 v[188:191], v150 offset:50176
	ds_read_b128 v[200:203], v150 offset:51200
	ds_read_b128 v[204:207], v150 offset:52224
	ds_read_b128 v[208:211], v150 offset:53248
	ds_read_b128 v[212:215], v150 offset:54272
	ds_read_b128 v[216:219], v150 offset:55296
	ds_read_b128 v[220:223], v150 offset:56320
	global_load_lds_dwordx4 v[148:149], off
	s_add_i32 m0, s14, 0x2000
	v_lshl_add_u64 v[148:149], v[224:225], 0, s[18:19]
	global_load_lds_dwordx4 v[148:149], off
	v_lshl_add_u64 v[148:149], v[226:227], 0, s[18:19]
	s_mov_b32 m0, s52
	s_nop 0
	global_load_lds_dwordx4 v[148:149], off
	v_lshl_add_u64 v[148:149], v[234:235], 0, s[18:19]
	s_mov_b32 m0, s53
	s_nop 0
	global_load_lds_dwordx4 v[148:149], off
	s_waitcnt vmcnt(6)
	s_waitcnt lgkmcnt(0)
	s_barrier
	s_setprio 1
	s_waitcnt lgkmcnt(0)
	v_mfma_f32_16x16x32_bf16 v[60:63], v[152:155], v[184:187], v[60:63]
	v_mfma_f32_16x16x32_bf16 v[48:51], v[160:163], v[184:187], v[48:51]
	v_mfma_f32_16x16x32_bf16 v[44:47], v[152:155], v[200:203], v[44:47]
	v_mfma_f32_16x16x32_bf16 v[32:35], v[160:163], v[200:203], v[32:35]
	v_mfma_f32_16x16x32_bf16 v[28:31], v[152:155], v[208:211], v[28:31]
	v_mfma_f32_16x16x32_bf16 v[16:19], v[160:163], v[208:211], v[16:19]
	v_mfma_f32_16x16x32_bf16 v[12:15], v[152:155], v[216:219], v[12:15]
	v_mfma_f32_16x16x32_bf16 v[4:7], v[160:163], v[216:219], v[4:7]
	v_mfma_f32_16x16x32_bf16 v[60:63], v[156:159], v[188:191], v[60:63]
	v_mfma_f32_16x16x32_bf16 v[48:51], v[164:167], v[188:191], v[48:51]
	v_mfma_f32_16x16x32_bf16 v[44:47], v[156:159], v[204:207], v[44:47]
	v_mfma_f32_16x16x32_bf16 v[32:35], v[164:167], v[204:207], v[32:35]
	v_mfma_f32_16x16x32_bf16 v[28:31], v[156:159], v[212:215], v[28:31]
	v_mfma_f32_16x16x32_bf16 v[16:19], v[164:167], v[212:215], v[16:19]
	v_mfma_f32_16x16x32_bf16 v[12:15], v[156:159], v[220:223], v[12:15]
	v_mfma_f32_16x16x32_bf16 v[4:7], v[164:167], v[220:223], v[4:7]
	v_mfma_f32_16x16x32_bf16 v[56:59], v[168:171], v[184:187], v[56:59]
	v_mfma_f32_16x16x32_bf16 v[52:55], v[176:179], v[184:187], v[52:55]
	v_mfma_f32_16x16x32_bf16 v[40:43], v[168:171], v[200:203], v[40:43]
	v_mfma_f32_16x16x32_bf16 v[36:39], v[176:179], v[200:203], v[36:39]
	v_mfma_f32_16x16x32_bf16 v[24:27], v[168:171], v[208:211], v[24:27]
	v_mfma_f32_16x16x32_bf16 v[20:23], v[176:179], v[208:211], v[20:23]
	v_mfma_f32_16x16x32_bf16 v[8:11], v[168:171], v[216:219], v[8:11]
	v_mfma_f32_16x16x32_bf16 v[0:3], v[176:179], v[216:219], v[0:3]
	v_mfma_f32_16x16x32_bf16 v[56:59], v[172:175], v[188:191], v[56:59]
	v_mfma_f32_16x16x32_bf16 v[52:55], v[180:183], v[188:191], v[52:55]
	v_mfma_f32_16x16x32_bf16 v[40:43], v[172:175], v[204:207], v[40:43]
	v_mfma_f32_16x16x32_bf16 v[36:39], v[180:183], v[204:207], v[36:39]
	v_mfma_f32_16x16x32_bf16 v[24:27], v[172:175], v[212:215], v[24:27]
	v_mfma_f32_16x16x32_bf16 v[20:23], v[180:183], v[212:215], v[20:23]
	v_mfma_f32_16x16x32_bf16 v[8:11], v[172:175], v[220:223], v[8:11]
	v_mfma_f32_16x16x32_bf16 v[0:3], v[180:183], v[220:223], v[0:3]
	s_setprio 0
	s_barrier
	s_add_i32 s60, s60, 2
	s_add_u32 s46, s46, 0x100
	s_addc_u32 s47, s47, 0
	s_add_u32 s6, s6, 0x100
	s_addc_u32 s7, s7, 0
	s_cmp_gt_u32 s60, 13
	s_cbranch_scc0 .LBB0_128
	s_and_b64 vcc, exec, s[20:21]
	s_cbranch_vccz .LBB0_131
	s_barrier

;     __device__ __forceinline__ void operator()(const f32x4 (&acc)[2][2][4][2], const Unit& u, int wr, int wc, int fr, int fq) const {
;     ...
;             } else {
;                 u32x2 rw[4][2][2];
; #pragma unroll
;                 for (int m = 0; m < 4; ++m) {
;                     const bf16_t* bp = hb + (size_t)(row0 + ai * HALF + m * 16) * 1024 + col0;
; #pragma unroll
;                     for (int bj = 0; bj < 2; ++bj)
; #pragma unroll
;                         for (int n = 0; n < 2; ++n) rw[m][bj][n] = *(const u32x2*)(bp + bj * HALF + n * 16);
;                 }
; #pragma unroll
;                 for (int m = 0; m < 4; ++m)
; #pragma unroll
;                     for (int bj = 0; bj < 2; ++bj)
; #pragma unroll
;                         for (int n = 0; n < 2; ++n) { const u32x2 r = rw[m][bj][n];
;                             v[m][bj][n] = (f32x4){__builtin_bit_cast(float, r.x << 16), __builtin_bit_cast(float, r.x & 0xffff0000u), __builtin_bit_cast(float, r.y << 16), __builtin_bit_cast(float, r.y & 0xffff0000u)}; }
.LBB0_241:
	v_lshlrev_b64 v[128:129], 11, v[212:213]
	v_lshlrev_b64 v[136:137], 11, v[226:227]
	v_lshlrev_b64 v[144:145], 11, v[224:225]
	v_lshl_add_u64 v[128:129], v[220:221], 0, v[128:129]
	v_lshl_add_u64 v[136:137], v[220:221], 0, v[136:137]
	v_lshl_add_u64 v[144:145], v[220:221], 0, v[144:145]
	global_load_dwordx2 v[130:131], v[128:129], off
	global_load_dwordx2 v[132:133], v[128:129], off offset:32
	global_load_dwordx2 v[134:135], v[128:129], off offset:256
	s_nop 0
	global_load_dwordx2 v[128:129], v[128:129], off offset:288
	s_nop 0
	global_load_dwordx2 v[138:139], v[136:137], off
	global_load_dwordx2 v[140:141], v[136:137], off offset:32
	global_load_dwordx2 v[142:143], v[136:137], off offset:256
	s_nop 0
	global_load_dwordx2 v[136:137], v[136:137], off offset:288
	s_nop 0
	global_load_dwordx2 v[146:147], v[144:145], off
	global_load_dwordx2 v[150:151], v[144:145], off offset:32
	global_load_dwordx2 v[154:155], v[144:145], off offset:256
	global_load_dwordx2 v[158:159], v[144:145], off offset:288
	v_lshlrev_b64 v[144:145], 11, v[222:223]
	v_lshl_add_u64 v[144:145], v[220:221], 0, v[144:145]
	global_load_dwordx2 v[238:239], v[144:145], off
	global_load_dwordx2 v[240:241], v[144:145], off offset:32
	global_load_dwordx2 v[242:243], v[144:145], off offset:256
	global_load_dwordx2 v[244:245], v[144:145], off offset:288
	s_waitcnt vmcnt(15)
	v_lshlrev_b32_e32 v176, 16, v130
	v_and_b32_e32 v177, 0xffff0000, v130
	v_lshlrev_b32_e32 v178, 16, v131
	v_and_b32_e32 v179, 0xffff0000, v131
	s_waitcnt vmcnt(14)
	v_lshlrev_b32_e32 v180, 16, v132
	v_and_b32_e32 v181, 0xffff0000, v132
	v_lshlrev_b32_e32 v182, 16, v133
	v_and_b32_e32 v183, 0xffff0000, v133
	s_waitcnt vmcnt(13)
	v_lshlrev_b32_e32 v184, 16, v134
	v_and_b32_e32 v185, 0xffff0000, v134
	v_lshlrev_b32_e32 v186, 16, v135
	v_and_b32_e32 v187, 0xffff0000, v135
	s_waitcnt vmcnt(12)
	v_lshlrev_b32_e32 v188, 16, v128
	v_and_b32_e32 v189, 0xffff0000, v128
	v_lshlrev_b32_e32 v190, 16, v129
	v_and_b32_e32 v191, 0xffff0000, v129
	s_waitcnt vmcnt(11)
	v_lshlrev_b32_e32 v160, 16, v138
	v_and_b32_e32 v161, 0xffff0000, v138
	v_lshlrev_b32_e32 v162, 16, v139
	v_and_b32_e32 v163, 0xffff0000, v139
	s_waitcnt vmcnt(10)
	v_lshlrev_b32_e32 v164, 16, v140
	v_and_b32_e32 v165, 0xffff0000, v140
	v_lshlrev_b32_e32 v166, 16, v141
	v_and_b32_e32 v167, 0xffff0000, v141
	s_waitcnt vmcnt(9)
	v_lshlrev_b32_e32 v168, 16, v142
	v_and_b32_e32 v169, 0xffff0000, v142
	v_lshlrev_b32_e32 v170, 16, v143
	v_and_b32_e32 v171, 0xffff0000, v143
	s_waitcnt vmcnt(8)
	v_lshlrev_b32_e32 v172, 16, v136
	v_and_b32_e32 v173, 0xffff0000, v136
	v_lshlrev_b32_e32 v174, 16, v137
	v_and_b32_e32 v175, 0xffff0000, v137
	s_waitcnt vmcnt(7)
	v_lshlrev_b32_e32 v144, 16, v146
	v_and_b32_e32 v145, 0xffff0000, v146
	v_lshlrev_b32_e32 v146, 16, v147
	v_and_b32_e32 v147, 0xffff0000, v147
	s_waitcnt vmcnt(6)
	v_lshlrev_b32_e32 v148, 16, v150
	v_and_b32_e32 v149, 0xffff0000, v150
	v_lshlrev_b32_e32 v150, 16, v151
	v_and_b32_e32 v151, 0xffff0000, v151
	s_waitcnt vmcnt(5)
	v_lshlrev_b32_e32 v152, 16, v154
	v_and_b32_e32 v153, 0xffff0000, v154
	v_lshlrev_b32_e32 v154, 16, v155
	v_and_b32_e32 v155, 0xffff0000, v155
	s_waitcnt vmcnt(4)
	v_lshlrev_b32_e32 v156, 16, v158
	v_and_b32_e32 v157, 0xffff0000, v158
	v_lshlrev_b32_e32 v158, 16, v159
	v_and_b32_e32 v159, 0xffff0000, v159
	s_waitcnt vmcnt(3)
	v_lshlrev_b32_e32 v128, 16, v238
	v_and_b32_e32 v129, 0xffff0000, v238
	v_lshlrev_b32_e32 v130, 16, v239
	v_and_b32_e32 v131, 0xffff0000, v239
	s_waitcnt vmcnt(2)
	v_lshlrev_b32_e32 v132, 16, v240
	v_and_b32_e32 v133, 0xffff0000, v240
	v_lshlrev_b32_e32 v134, 16, v241
	v_and_b32_e32 v135, 0xffff0000, v241
	s_waitcnt vmcnt(1)
	v_lshlrev_b32_e32 v136, 16, v242
	v_and_b32_e32 v137, 0xffff0000, v242
	v_lshlrev_b32_e32 v138, 16, v243
	v_and_b32_e32 v139, 0xffff0000, v243
	s_waitcnt vmcnt(0)
	v_lshlrev_b32_e32 v140, 16, v244
	v_and_b32_e32 v141, 0xffff0000, v244
	v_lshlrev_b32_e32 v142, 16, v245
	v_and_b32_e32 v143, 0xffff0000, v245

;     __device__ __forceinline__ void operator()(const f32x4 (&acc)[2][2][4][2], const Unit& u, int wr, int wc, int fr, int fq) const {
;     ...
;             } else {
;                 u32x2 rw[4][2][2];
; #pragma unroll
;                 for (int m = 0; m < 4; ++m) {
;                     const bf16_t* bp = hb + (size_t)(row0 + ai * HALF + m * 16) * 1024 + col0;
; #pragma unroll
;                     for (int bj = 0; bj < 2; ++bj)
; #pragma unroll
;                         for (int n = 0; n < 2; ++n) rw[m][bj][n] = *(const u32x2*)(bp + bj * HALF + n * 16);
;                 }
; #pragma unroll
;                 for (int m = 0; m < 4; ++m)
; #pragma unroll
;                     for (int bj = 0; bj < 2; ++bj)
; #pragma unroll
;                         for (int n = 0; n < 2; ++n) { const u32x2 r = rw[m][bj][n];
;                             v[m][bj][n] = (f32x4){__builtin_bit_cast(float, r.x << 16), __builtin_bit_cast(float, r.x & 0xffff0000u), __builtin_bit_cast(float, r.y << 16), __builtin_bit_cast(float, r.y & 0xffff0000u)}; }
.LBB0_266:
	v_lshlrev_b64 v[72:73], 11, v[212:213]
	v_lshl_add_u64 v[72:73], v[220:221], 0, v[72:73]
	v_lshlrev_b64 v[64:65], 11, v[128:129]
	s_mov_b64 s[4:5], 0x48000
	v_add_co_u32_e32 v84, vcc, 0x48000, v72
	v_lshl_add_u64 v[64:65], v[220:221], 0, v[64:65]
	v_lshl_add_u64 v[74:75], v[72:73], 0, s[4:5]
	v_addc_co_u32_e32 v85, vcc, 0, v73, vcc
	global_load_dwordx2 v[66:67], v[64:65], off
	global_load_dwordx2 v[68:69], v[64:65], off offset:32
	global_load_dwordx2 v[70:71], v[64:65], off offset:256
	s_nop 0
	global_load_dwordx2 v[64:65], v[64:65], off offset:288
	s_nop 0
	global_load_dwordx2 v[76:77], v[74:75], off offset:32
	global_load_dwordx2 v[78:79], v[74:75], off offset:256
	global_load_dwordx2 v[88:89], v[84:85], off
	v_add_co_u32_e32 v84, vcc, 0x50000, v72
	s_mov_b64 s[4:5], 0x50000
	s_nop 0
	v_addc_co_u32_e32 v85, vcc, 0, v73, vcc
	v_lshl_add_u64 v[80:81], v[72:73], 0, s[4:5]
	global_load_dwordx2 v[90:91], v[84:85], off
	v_add_co_u32_e32 v84, vcc, 0x58000, v72
	s_mov_b64 s[4:5], 0x58000
	s_nop 0
	v_addc_co_u32_e32 v85, vcc, 0, v73, vcc
	v_lshl_add_u64 v[72:73], v[72:73], 0, s[4:5]
	s_waitcnt lgkmcnt(0)
	global_load_dwordx2 v[82:83], v[80:81], off offset:32
	global_load_dwordx2 v[86:87], v[80:81], off offset:256
	global_load_dwordx2 v[130:131], v[80:81], off offset:288
	global_load_dwordx2 v[132:133], v[84:85], off
	s_waitcnt vmcnt(11)
	v_lshlrev_b32_e32 v112, 16, v66
	global_load_dwordx2 v[74:75], v[74:75], off offset:288
	s_nop 0
	global_load_dwordx2 v[134:135], v[72:73], off offset:32
	global_load_dwordx2 v[136:137], v[72:73], off offset:256
	global_load_dwordx2 v[138:139], v[72:73], off offset:288
	v_and_b32_e32 v113, 0xffff0000, v66
	v_lshlrev_b32_e32 v114, 16, v67
	v_and_b32_e32 v115, 0xffff0000, v67
	s_waitcnt vmcnt(14)
	v_lshlrev_b32_e32 v116, 16, v68
	v_and_b32_e32 v117, 0xffff0000, v68
	v_lshlrev_b32_e32 v118, 16, v69
	v_and_b32_e32 v119, 0xffff0000, v69
	s_waitcnt vmcnt(13)
	v_lshlrev_b32_e32 v120, 16, v70
	v_and_b32_e32 v121, 0xffff0000, v70
	v_lshlrev_b32_e32 v122, 16, v71
	v_and_b32_e32 v123, 0xffff0000, v71
	s_waitcnt vmcnt(12)
	v_lshlrev_b32_e32 v124, 16, v64
	v_and_b32_e32 v125, 0xffff0000, v64
	v_lshlrev_b32_e32 v126, 16, v65
	v_and_b32_e32 v127, 0xffff0000, v65
	s_waitcnt vmcnt(11)
	v_lshlrev_b32_e32 v96, 16, v76
	v_and_b32_e32 v97, 0xffff0000, v76
	v_lshlrev_b32_e32 v98, 16, v77
	v_and_b32_e32 v99, 0xffff0000, v77
	s_waitcnt vmcnt(10)
	v_lshlrev_b32_e32 v100, 16, v78
	v_and_b32_e32 v101, 0xffff0000, v78
	v_lshlrev_b32_e32 v102, 16, v79
	v_and_b32_e32 v103, 0xffff0000, v79
	s_waitcnt vmcnt(7)
	v_lshlrev_b32_e32 v80, 16, v82
	v_and_b32_e32 v81, 0xffff0000, v82
	v_lshlrev_b32_e32 v82, 16, v83
	v_and_b32_e32 v83, 0xffff0000, v83
	s_waitcnt vmcnt(6)
	v_lshlrev_b32_e32 v84, 16, v86
	v_and_b32_e32 v85, 0xffff0000, v86
	v_lshlrev_b32_e32 v86, 16, v87
	v_and_b32_e32 v87, 0xffff0000, v87
	v_lshlrev_b32_e32 v108, 16, v88
	v_and_b32_e32 v109, 0xffff0000, v88
	v_lshlrev_b32_e32 v110, 16, v89
	v_and_b32_e32 v111, 0xffff0000, v89
	v_lshlrev_b32_e32 v92, 16, v90
	v_and_b32_e32 v93, 0xffff0000, v90
	v_lshlrev_b32_e32 v94, 16, v91
	v_and_b32_e32 v95, 0xffff0000, v91
	s_waitcnt vmcnt(5)
	v_lshlrev_b32_e32 v88, 16, v130
	v_and_b32_e32 v89, 0xffff0000, v130
	v_lshlrev_b32_e32 v90, 16, v131
	v_and_b32_e32 v91, 0xffff0000, v131
	s_waitcnt vmcnt(4)
	v_lshlrev_b32_e32 v64, 16, v132
	v_and_b32_e32 v65, 0xffff0000, v132
	v_lshlrev_b32_e32 v66, 16, v133
	v_and_b32_e32 v67, 0xffff0000, v133
	s_waitcnt vmcnt(2)
	v_lshlrev_b32_e32 v68, 16, v134
	v_lshlrev_b32_e32 v104, 16, v74
	v_and_b32_e32 v105, 0xffff0000, v74
	v_lshlrev_b32_e32 v106, 16, v75
	v_and_b32_e32 v107, 0xffff0000, v75
	v_and_b32_e32 v69, 0xffff0000, v134
	v_lshlrev_b32_e32 v70, 16, v135
	v_and_b32_e32 v71, 0xffff0000, v135
	s_waitcnt vmcnt(1)
	v_lshlrev_b32_e32 v72, 16, v136
	v_and_b32_e32 v73, 0xffff0000, v136
	v_lshlrev_b32_e32 v74, 16, v137
	v_and_b32_e32 v75, 0xffff0000, v137
	s_waitcnt vmcnt(0)
	v_lshlrev_b32_e32 v76, 16, v138
	v_and_b32_e32 v77, 0xffff0000, v138
	v_lshlrev_b32_e32 v78, 16, v139
	v_and_b32_e32 v79, 0xffff0000, v139
